# lever 1 counted wait: at residual GEMM phase entry the unpack waits vmcnt(8) (residual-tile loads only) instead of vmcnt(0), so it overlaps the first eight tile DMAs
# speedup vs baseline: 1.0110x; 1.0012x over previous
; __device__ __forceinline__ float bf_lo(unsigned w) { return __uint_as_float(w << 16); }
; __device__ __forceinline__ float bf_hi(unsigned w) { return __uint_as_float(w & 0xffff0000u); }
; #define PG8_STAGE(bufoff, gbase, voff) do { _Pragma("unroll") for (int _i = 0; _i < 2; ++_i) \
;         __builtin_amdgcn_global_load_lds((const unsigned*)((const char*)(gbase) + (voff)[_i]), (LAS unsigned*)(lds + (bufoff) + ldsw + _i * 8192), 16, 0, 0); } while (0)
; #define PG8_WAIT_V(n) asm volatile("s_waitcnt vmcnt(" #n ")" ::: "memory")
; #define PG8_BAR __builtin_amdgcn_s_barrier()
;     __device__ __forceinline__ void init(f32x4 (&acc)[2][2][4][2], const pg8::Unit&, int, int, int, int) const { acc_zero(acc); }
;     __device__ __forceinline__ void init(f32x4 (&acc)[2][2][4][2], const pg8::Unit&, int, int, int, int) const { acc_zero(acc); }
;     __device__ __forceinline__ void init(f32x4 (&acc)[2][2][4][2], const pg8::Unit&, int, int, int, int) const { acc_zero(acc); }
; template <class Epi, class Sched>
; __device__ __forceinline__ void gemm_phase(LAS unsigned char* lds, const Gemm g, const Sched& S, const Epi& E) {
;     ...
;     E.init(acc, cur, wr, wc, fr, fq);
;     bf16x8 At[4][2], B0[2][2], B1[2][2];
;     const char* cA = (const char*)g.A + (size_t)cur.pm * tstepA + (size_t)cur.pn * g.a_pn_off * 2; const char* cB = (const char*)g.Bt + (size_t)cur.pn * tstepB;
;     PG8_STAGE(PG8_SB(0, 0), cB, voffB); PG8_STAGE(PG8_SB(0, 1), cB + hstepB, voffB); PG8_STAGE(PG8_SA(0, 0), cA, voffA); PG8_STAGE(PG8_SA(0, 1), cA + hstepA, voffA);
;     if (wr == 1) PG8_BAR;
;     PG8_WAIT_V(2); PG8_BAR;
;     PG8_STAGE(PG8_SB(1, 0), cB + kstep, voffB); PG8_STAGE(PG8_SA(1, 0), cA + kstep, voffA); PG8_STAGE(PG8_SB(1, 1), cB + hstepB + kstep, voffB);
;     PG8_WAIT_V(6); PG8_BAR;
;     __device__ __forceinline__ void init(f32x4 (&acc)[2][2][4][2], const pg8::Unit& u, int wr, int wc, int fr, int fq) const {
;     ...
;                     if (BASE_F32) { acc[ai][bj][m][0] = *(const f32x4*)(base32 + off); acc[ai][bj][m][1] = *(const f32x4*)(base32 + off + 4); }
;                     else { const u32x4 w = *(const u32x4*)(xb + off);
;                         acc[ai][bj][m][0] = (f32x4){bf_lo(w.x), bf_hi(w.x), bf_lo(w.y), bf_hi(w.y)}; acc[ai][bj][m][1] = (f32x4){bf_lo(w.z), bf_hi(w.z), bf_lo(w.w), bf_hi(w.w)}; }
.LBB0_584:
	v_mov_b32_e32 v133, v0
	s_waitcnt vmcnt(8)
	v_lshlrev_b32_e32 v114, 16, v62
	v_and_b32_e32 v115, 0xffff0000, v62
	v_lshlrev_b32_e32 v116, 16, v63
	v_and_b32_e32 v117, 0xffff0000, v63
	v_lshlrev_b32_e32 v118, 16, v64
	v_and_b32_e32 v119, 0xffff0000, v64
	v_lshlrev_b32_e32 v120, 16, v65
	v_and_b32_e32 v121, 0xffff0000, v65
	v_lshlrev_b32_e32 v62, 16, v34
	v_and_b32_e32 v63, 0xffff0000, v34
	v_lshlrev_b32_e32 v64, 16, v35
	v_and_b32_e32 v65, 0xffff0000, v35
	v_lshlrev_b32_e32 v66, 16, v36
	v_and_b32_e32 v67, 0xffff0000, v36
	v_lshlrev_b32_e32 v68, 16, v37
	v_and_b32_e32 v69, 0xffff0000, v37
	v_lshlrev_b32_e32 v70, 16, v22
	v_and_b32_e32 v71, 0xffff0000, v22
	v_lshlrev_b32_e32 v72, 16, v23
	v_and_b32_e32 v73, 0xffff0000, v23
	v_lshlrev_b32_e32 v78, 16, v24
	v_and_b32_e32 v79, 0xffff0000, v24
	v_lshlrev_b32_e32 v80, 16, v25
	v_and_b32_e32 v81, 0xffff0000, v25
	v_lshlrev_b32_e32 v22, 16, v30
	v_and_b32_e32 v23, 0xffff0000, v30
	v_lshlrev_b32_e32 v24, 16, v31
	v_and_b32_e32 v25, 0xffff0000, v31
	v_lshlrev_b32_e32 v34, 16, v32
	v_and_b32_e32 v35, 0xffff0000, v32
	v_lshlrev_b32_e32 v36, 16, v33
	v_and_b32_e32 v37, 0xffff0000, v33
	v_lshlrev_b32_e32 v30, 16, v54
	v_and_b32_e32 v31, 0xffff0000, v54
	v_lshlrev_b32_e32 v32, 16, v55
	v_and_b32_e32 v33, 0xffff0000, v55
	v_lshl_add_u64 v[54:55], s[86:87], 0, v[132:133]
	v_mov_b32_e32 v137, v0
	v_lshlrev_b32_e32 v122, 16, v58
	v_and_b32_e32 v123, 0xffff0000, v58
	v_lshlrev_b32_e32 v124, 16, v59
	v_and_b32_e32 v125, 0xffff0000, v59
	v_lshl_add_u64 v[58:59], s[86:87], 0, v[136:137]
	v_mov_b32_e32 v131, v0
	s_add_i32 m0, s35, 0x18000
	v_lshl_add_u64 v[54:55], v[54:55], 0, s[62:63]
	v_lshl_add_u64 v[76:77], s[18:19], 0, v[130:131]
	v_mov_b32_e32 v135, v0
	s_waitcnt vmcnt(2)
	s_barrier
	global_load_lds_dwordx4 v[54:55], off
	v_lshl_add_u64 v[54:55], v[58:59], 0, s[62:63]
	s_add_i32 m0, s35, 0x1a000
	s_add_i32 s41, s35, 0x8000
	v_lshl_add_u64 v[82:83], s[18:19], 0, v[134:135]
	global_load_lds_dwordx4 v[54:55], off
	v_lshl_add_u64 v[54:55], v[76:77], 0, s[62:63]
	s_mov_b32 m0, s41
	s_add_i32 s42, s35, 0xa000
	v_lshlrev_b32_e32 v126, 16, v60
	v_and_b32_e32 v127, 0xffff0000, v60
	v_lshlrev_b32_e32 v128, 16, v61
	v_and_b32_e32 v129, 0xffff0000, v61
	v_lshl_add_u64 v[60:61], s[20:21], 0, v[132:133]
	global_load_lds_dwordx4 v[54:55], off
	v_lshl_add_u64 v[54:55], v[82:83], 0, s[62:63]
	s_mov_b32 m0, s42
	v_lshl_add_u64 v[74:75], s[20:21], 0, v[136:137]
	global_load_lds_dwordx4 v[54:55], off
	s_add_i32 m0, s35, 0x1c000
	v_lshl_add_u64 v[54:55], v[60:61], 0, s[62:63]
	global_load_lds_dwordx4 v[54:55], off
	v_lshl_add_u64 v[54:55], v[74:75], 0, s[62:63]
	s_add_i32 m0, s35, 0x1e000
	v_or_b32_e32 v1, s49, v140
	global_load_lds_dwordx4 v[54:55], off
	v_lshlrev_b32_e32 v141, 6, v1
	v_lshlrev_b32_e32 v142, 4, v138
	s_movk_i32 s12, 0x3c0
	v_lshlrev_b32_e32 v143, 2, v1
	s_lshr_b32 s48, s1, 6
	v_and_or_b32 v141, v141, s12, v142
	s_lshl_b32 s20, s43, 13
	v_and_b32_e32 v143, 32, v143
	v_bitop3_b32 v143, v141, s20, v143 bitop3:0xde
	v_lshl_or_b32 v141, v140, 6, v142
	s_lshl_b32 s20, s28, 12
	v_lshlrev_b32_e32 v140, 2, v140
	s_waitcnt vmcnt(6)
	s_add_i32 s43, s48, -2
	v_and_b32_e32 v140, 32, v140
	s_cmpk_lt_u32 s36, 0x100
	v_lshlrev_b32_e32 v94, 16, v46
	v_and_b32_e32 v95, 0xffff0000, v46
	v_lshlrev_b32_e32 v96, 16, v47
	v_and_b32_e32 v97, 0xffff0000, v47
	v_lshlrev_b32_e32 v98, 16, v48
	v_and_b32_e32 v99, 0xffff0000, v48
	v_lshlrev_b32_e32 v100, 16, v49
	v_and_b32_e32 v101, 0xffff0000, v49
	v_lshlrev_b32_e32 v102, 16, v38
	v_and_b32_e32 v103, 0xffff0000, v38
	v_lshlrev_b32_e32 v104, 16, v39
	v_and_b32_e32 v105, 0xffff0000, v39
	v_lshlrev_b32_e32 v106, 16, v40
	v_and_b32_e32 v107, 0xffff0000, v40
	v_lshlrev_b32_e32 v108, 16, v41
	v_and_b32_e32 v109, 0xffff0000, v41
	v_lshlrev_b32_e32 v38, 16, v14
	v_and_b32_e32 v39, 0xffff0000, v14
	v_lshlrev_b32_e32 v40, 16, v15
	v_and_b32_e32 v41, 0xffff0000, v15
	v_lshlrev_b32_e32 v46, 16, v16
	v_and_b32_e32 v47, 0xffff0000, v16
	v_lshlrev_b32_e32 v48, 16, v17
	v_and_b32_e32 v49, 0xffff0000, v17
	v_lshlrev_b32_e32 v14, 16, v26
	v_and_b32_e32 v15, 0xffff0000, v26
	v_lshlrev_b32_e32 v16, 16, v27
	v_and_b32_e32 v17, 0xffff0000, v27
	v_lshlrev_b32_e32 v26, 16, v28
	v_and_b32_e32 v27, 0xffff0000, v28
	v_lshlrev_b32_e32 v28, 16, v29
	v_and_b32_e32 v29, 0xffff0000, v29
	v_lshlrev_b32_e32 v110, 16, v56
	v_and_b32_e32 v111, 0xffff0000, v56
	v_lshlrev_b32_e32 v112, 16, v57
	v_and_b32_e32 v113, 0xffff0000, v57
	v_lshlrev_b32_e32 v74, 16, v50
	v_and_b32_e32 v75, 0xffff0000, v50
	v_lshlrev_b32_e32 v76, 16, v51
	v_and_b32_e32 v77, 0xffff0000, v51
	v_lshlrev_b32_e32 v82, 16, v52
	v_and_b32_e32 v83, 0xffff0000, v52
	v_lshlrev_b32_e32 v84, 16, v53
	v_and_b32_e32 v85, 0xffff0000, v53
	v_lshlrev_b32_e32 v86, 16, v42
	v_and_b32_e32 v87, 0xffff0000, v42
	v_lshlrev_b32_e32 v88, 16, v43
	v_and_b32_e32 v89, 0xffff0000, v43
	v_lshlrev_b32_e32 v90, 16, v44
	v_and_b32_e32 v91, 0xffff0000, v44
	v_lshlrev_b32_e32 v92, 16, v45
	v_and_b32_e32 v93, 0xffff0000, v45
	v_lshlrev_b32_e32 v42, 16, v10
	v_and_b32_e32 v43, 0xffff0000, v10
	v_lshlrev_b32_e32 v44, 16, v11
	v_and_b32_e32 v45, 0xffff0000, v11
	v_lshlrev_b32_e32 v50, 16, v12
	v_and_b32_e32 v51, 0xffff0000, v12
	v_lshlrev_b32_e32 v52, 16, v13
	v_and_b32_e32 v53, 0xffff0000, v13
	v_lshlrev_b32_e32 v54, 16, v2
	v_and_b32_e32 v55, 0xffff0000, v2
	v_lshlrev_b32_e32 v56, 16, v3
	v_and_b32_e32 v57, 0xffff0000, v3
	v_lshlrev_b32_e32 v58, 16, v4
	v_and_b32_e32 v59, 0xffff0000, v4
	v_lshlrev_b32_e32 v60, 16, v5
	v_and_b32_e32 v61, 0xffff0000, v5
	v_lshlrev_b32_e32 v2, 16, v6
	v_and_b32_e32 v3, 0xffff0000, v6
	v_lshlrev_b32_e32 v4, 16, v7
	v_and_b32_e32 v5, 0xffff0000, v7
	v_lshlrev_b32_e32 v6, 16, v8
	v_and_b32_e32 v7, 0xffff0000, v8
	v_lshlrev_b32_e32 v8, 16, v9
	v_and_b32_e32 v9, 0xffff0000, v9
	v_lshlrev_b32_e32 v10, 16, v18
	v_and_b32_e32 v11, 0xffff0000, v18
	v_lshlrev_b32_e32 v12, 16, v19
	v_and_b32_e32 v13, 0xffff0000, v19
	v_lshlrev_b32_e32 v18, 16, v20
	v_and_b32_e32 v19, 0xffff0000, v20
	v_lshlrev_b32_e32 v20, 16, v21
	v_and_b32_e32 v21, 0xffff0000, v21
	v_bitop3_b32 v146, v141, s20, v140 bitop3:0xde
	s_cselect_b64 s[84:85], -1, 0
	s_mov_b32 s49, 0
	v_cmp_eq_u32_e64 s[66:67], 0, v138
	v_or_b32_e32 v147, s37, v139
	v_lshl_add_u64 v[138:139], s[80:81], 0, v[130:131]
	v_lshl_add_u64 v[140:141], s[80:81], 0, v[134:135]
	v_add_u32_e32 v148, 0, v143
	v_readlane_b32 s54, v250, 21
	v_readlane_b32 s89, v250, 23
	s_barrier
	s_branch .LBB0_587

; __device__ __forceinline__ float bf_lo(unsigned w) { return __uint_as_float(w << 16); }
; __device__ __forceinline__ float bf_hi(unsigned w) { return __uint_as_float(w & 0xffff0000u); }
; #define PG8_STAGE(bufoff, gbase, voff) do { _Pragma("unroll") for (int _i = 0; _i < 2; ++_i) \
;         __builtin_amdgcn_global_load_lds((const unsigned*)((const char*)(gbase) + (voff)[_i]), (LAS unsigned*)(lds + (bufoff) + ldsw + _i * 8192), 16, 0, 0); } while (0)
; #define PG8_WAIT_V(n) asm volatile("s_waitcnt vmcnt(" #n ")" ::: "memory")
; #define PG8_BAR __builtin_amdgcn_s_barrier()
; template <class Epi, class Sched>
; __device__ __forceinline__ void gemm_phase(LAS unsigned char* lds, const Gemm g, const Sched& S, const Epi& E) {
;     ...
;     PG8_STAGE(PG8_SB(0, 0), cB, voffB); PG8_STAGE(PG8_SB(0, 1), cB + hstepB, voffB); PG8_STAGE(PG8_SA(0, 0), cA, voffA); PG8_STAGE(PG8_SA(0, 1), cA + hstepA, voffA);
;     if (wr == 1) PG8_BAR;
;     PG8_WAIT_V(2); PG8_BAR;
;     PG8_STAGE(PG8_SB(1, 0), cB + kstep, voffB); PG8_STAGE(PG8_SA(1, 0), cA + kstep, voffA); PG8_STAGE(PG8_SB(1, 1), cB + hstepB + kstep, voffB);
;     PG8_WAIT_V(6); PG8_BAR;
;     __device__ __forceinline__ void init(f32x4 (&acc)[2][2][4][2], const pg8::Unit& u, int wr, int wc, int fr, int fq) const {
;     ...
;                     if (BASE_F32) { acc[ai][bj][m][0] = *(const f32x4*)(base32 + off); acc[ai][bj][m][1] = *(const f32x4*)(base32 + off + 4); }
;                     else { const u32x4 w = *(const u32x4*)(xb + off);
;                         acc[ai][bj][m][0] = (f32x4){bf_lo(w.x), bf_hi(w.x), bf_lo(w.y), bf_hi(w.y)}; acc[ai][bj][m][1] = (f32x4){bf_lo(w.z), bf_hi(w.z), bf_lo(w.w), bf_hi(w.w)}; }
;                 }
;         if (AFFINE) {
; #pragma unroll
;             for (int bj = 0; bj < 2; ++bj)
; #pragma unroll
;                 for (int n = 0; n < 2; ++n) { const f32x4 bs = *(const f32x4*)(bias + col0 + bj * 128 + 4 * n) * *(const f32x4*)(scale + col0 + bj * 128 + 4 * n);
; #pragma unroll
;                     for (int ai = 0; ai < 2; ++ai)
; #pragma unroll
;                         for (int m = 0; m < 4; ++m) acc[ai][bj][m][n] += bs; }
.LBB0_694:
	v_mov_b32_e32 v193, v0
	v_lshl_add_u64 v[202:203], s[18:19], 0, v[192:193]
	v_mov_b32_e32 v197, v0
	v_lshl_add_u64 v[204:205], s[18:19], 0, v[196:197]
	v_mov_b32_e32 v191, v0
	s_waitcnt vmcnt(8)
	v_pk_fma_f32 v[14:15], v[86:87], v[98:99], v[10:11]
	v_pk_fma_f32 v[10:11], v[86:87], v[98:99], v[26:27]
	s_add_i32 m0, s31, 0x18000
	v_lshl_add_u64 v[26:27], v[202:203], 0, s[62:63]
	v_lshl_add_u64 v[208:209], s[86:87], 0, v[190:191]
	v_mov_b32_e32 v195, v0
	s_waitcnt vmcnt(2)
	s_barrier
	global_load_lds_dwordx4 v[26:27], off
	v_lshl_add_u64 v[26:27], v[204:205], 0, s[62:63]
	s_add_i32 m0, s31, 0x1a000
	s_add_i32 s41, s31, 0x8000
	v_lshl_add_u64 v[206:207], s[86:87], 0, v[194:195]
	global_load_lds_dwordx4 v[26:27], off
	v_lshl_add_u64 v[26:27], v[208:209], 0, s[62:63]
	s_mov_b32 m0, s41
	s_add_i32 s42, s31, 0xa000
	v_lshl_add_u64 v[200:201], s[20:21], 0, v[192:193]
	global_load_lds_dwordx4 v[26:27], off
	v_lshl_add_u64 v[26:27], v[206:207], 0, s[62:63]
	s_mov_b32 m0, s42
	v_lshl_add_u64 v[198:199], s[20:21], 0, v[196:197]
	global_load_lds_dwordx4 v[26:27], off
	s_add_i32 m0, s31, 0x1c000
	v_lshl_add_u64 v[26:27], v[200:201], 0, s[62:63]
	global_load_lds_dwordx4 v[26:27], off
	v_lshl_add_u64 v[26:27], v[198:199], 0, s[62:63]
	s_add_i32 m0, s31, 0x1e000
	v_or_b32_e32 v1, s43, v219
	global_load_lds_dwordx4 v[26:27], off
	v_pk_fma_f32 v[16:17], v[88:89], v[100:101], v[12:13]
	v_pk_fma_f32 v[12:13], v[88:89], v[100:101], v[28:29]
	v_pk_fma_f32 v[28:29], v[88:89], v[100:101], v[20:21]
	v_pk_fma_f32 v[26:27], v[86:87], v[98:99], v[18:19]
	v_pk_fma_f32 v[20:21], v[88:89], v[100:101], v[76:77]
	v_pk_fma_f32 v[18:19], v[86:87], v[98:99], v[74:75]
	v_pk_fma_f32 v[76:77], v[164:165], v[168:169], v[64:65]
	v_pk_fma_f32 v[74:75], v[162:163], v[166:167], v[62:63]
	v_pk_fma_f32 v[64:65], v[164:165], v[168:169], v[84:85]
	v_pk_fma_f32 v[62:63], v[162:163], v[166:167], v[82:83]
	v_pk_fma_f32 v[84:85], v[156:157], v[160:161], v[72:73]
	v_pk_fma_f32 v[82:83], v[154:155], v[158:159], v[70:71]
	v_pk_fma_f32 v[72:73], v[156:157], v[160:161], v[104:105]
	v_pk_fma_f32 v[70:71], v[154:155], v[158:159], v[102:103]
	v_pk_fma_f32 v[104:105], v[148:149], v[152:153], v[92:93]
	v_pk_fma_f32 v[102:103], v[146:147], v[150:151], v[90:91]
	v_pk_fma_f32 v[92:93], v[148:149], v[152:153], v[132:133]
	v_pk_fma_f32 v[90:91], v[146:147], v[150:151], v[130:131]
	v_lshlrev_b32_e32 v130, 6, v1
	v_lshlrev_b32_e32 v131, 4, v217
	s_movk_i32 s14, 0x3c0
	v_lshlrev_b32_e32 v132, 2, v1
	s_lshr_b32 s1, s1, 6
	v_and_or_b32 v130, v130, s14, v131
	s_lshl_b32 s20, s37, 13
	v_and_b32_e32 v132, 32, v132
	v_bitop3_b32 v130, v130, s20, v132 bitop3:0xde
	s_lshl_b32 s20, s8, 12
	v_lshlrev_b32_e32 v132, 2, v219
	s_waitcnt vmcnt(6)
	s_add_i32 s43, s1, -2
	v_lshl_or_b32 v131, v219, 6, v131
	v_and_b32_e32 v132, 32, v132
	s_cmpk_lt_u32 s36, 0x100
	v_readlane_b32 s72, v251, 63
	v_pk_fma_f32 v[36:37], v[88:89], v[100:101], v[4:5]
	v_pk_fma_f32 v[34:35], v[86:87], v[98:99], v[2:3]
	v_pk_fma_f32 v[24:25], v[88:89], v[100:101], v[8:9]
	v_pk_fma_f32 v[22:23], v[86:87], v[98:99], v[6:7]
	v_pk_fma_f32 v[8:9], v[88:89], v[100:101], v[112:113]
	v_pk_fma_f32 v[6:7], v[86:87], v[98:99], v[110:111]
	v_pk_fma_f32 v[4:5], v[88:89], v[100:101], v[172:173]
	v_pk_fma_f32 v[2:3], v[86:87], v[98:99], v[170:171]
	v_pk_fma_f32 v[112:113], v[164:165], v[168:169], v[32:33]
	v_pk_fma_f32 v[110:111], v[162:163], v[166:167], v[30:31]
	v_pk_fma_f32 v[100:101], v[164:165], v[168:169], v[44:45]
	v_pk_fma_f32 v[98:99], v[162:163], v[166:167], v[42:43]
	v_pk_fma_f32 v[88:89], v[164:165], v[168:169], v[52:53]
	v_pk_fma_f32 v[86:87], v[162:163], v[166:167], v[50:51]
	v_pk_fma_f32 v[52:53], v[164:165], v[168:169], v[96:97]
	v_pk_fma_f32 v[50:51], v[162:163], v[166:167], v[94:95]
	v_pk_fma_f32 v[44:45], v[164:165], v[168:169], v[108:109]
	v_pk_fma_f32 v[42:43], v[162:163], v[166:167], v[106:107]
	v_pk_fma_f32 v[32:33], v[164:165], v[168:169], v[120:121]
	v_pk_fma_f32 v[30:31], v[162:163], v[166:167], v[118:119]
	v_pk_fma_f32 v[120:121], v[156:157], v[160:161], v[40:41]
	v_pk_fma_f32 v[118:119], v[154:155], v[158:159], v[38:39]
	v_pk_fma_f32 v[108:109], v[156:157], v[160:161], v[48:49]
	v_pk_fma_f32 v[106:107], v[154:155], v[158:159], v[46:47]
	v_pk_fma_f32 v[96:97], v[156:157], v[160:161], v[60:61]
	v_pk_fma_f32 v[94:95], v[154:155], v[158:159], v[58:59]
	v_pk_fma_f32 v[60:61], v[156:157], v[160:161], v[116:117]
	v_pk_fma_f32 v[58:59], v[154:155], v[158:159], v[114:115]
	v_pk_fma_f32 v[48:49], v[156:157], v[160:161], v[124:125]
	v_pk_fma_f32 v[46:47], v[154:155], v[158:159], v[122:123]
	v_pk_fma_f32 v[40:41], v[156:157], v[160:161], v[128:129]
	v_pk_fma_f32 v[38:39], v[154:155], v[158:159], v[126:127]
	v_pk_fma_f32 v[128:129], v[148:149], v[152:153], v[56:57]
	v_pk_fma_f32 v[126:127], v[146:147], v[150:151], v[54:55]
	v_pk_fma_f32 v[124:125], v[148:149], v[152:153], v[68:69]
	v_pk_fma_f32 v[122:123], v[146:147], v[150:151], v[66:67]
	v_pk_fma_f32 v[116:117], v[148:149], v[152:153], v[80:81]
	v_pk_fma_f32 v[114:115], v[146:147], v[150:151], v[78:79]
	v_pk_fma_f32 v[80:81], v[148:149], v[152:153], v[136:137]
	v_pk_fma_f32 v[78:79], v[146:147], v[150:151], v[134:135]
	v_pk_fma_f32 v[68:69], v[148:149], v[152:153], v[140:141]
	v_pk_fma_f32 v[66:67], v[146:147], v[150:151], v[138:139]
	v_pk_fma_f32 v[56:57], v[148:149], v[152:153], v[144:145]
	v_pk_fma_f32 v[54:55], v[146:147], v[150:151], v[142:143]
	v_bitop3_b32 v202, v131, s20, v132 bitop3:0xde
	s_cselect_b64 s[36:37], -1, 0
	s_mov_b32 s48, 0
	v_cmp_eq_u32_e64 s[66:67], 0, v217
	v_or_b32_e32 v203, s49, v218
	v_lshl_add_u64 v[198:199], s[80:81], 0, v[190:191]
	v_lshl_add_u64 v[200:201], s[80:81], 0, v[194:195]
	v_add_u32_e32 v204, 0, v130
	v_readlane_b32 s54, v250, 21
	v_readlane_b32 s81, v250, 23
	s_mov_b64 s[64:65], s[12:13]
	v_readlane_b32 s73, v252, 0
	s_mov_b32 s14, 0x3fb8aa3b
	s_barrier
	s_branch .LBB0_697
